# PH14 norm_rows: gain loads hoisted out of the store-load-wait chain
# speedup vs baseline: 1.0390x; 1.0004x over previous
; #define p (*kparams())
; __device__ __forceinline__ void norm_rows(CParams& p, int mode, const float* gain, int nrows) {
;     ...
;     for (int row = gw; row < nrows; row += NW) {
;         f32x4 v[8];
;         if (mode == 0) {
;             const float* src = nullptr;
;             if (row < MX) src = p.in[0] + (size_t)row * D;
;             else { const int i = (row - MX) & 127; if (i >= 112) src = p.in[1] + (size_t)(i - 112) * D; }
; #pragma unroll
;             for (int j = 0; j < 8; ++j) { v[j] = src ? *(const f32x4*)(src + (lane + 64 * j) * 4) : (f32x4){0.f, 0.f, 0.f, 0.f}; if (row >= MX) *(f32x4*)(H + (size_t)row * D + (lane + 64 * j) * 4) = v[j]; }
;         } else {
; #pragma unroll
;             for (int j = 0; j < 8; ++j) v[j] = *(const f32x4*)(H + (size_t)row * D + (lane + 64 * j) * 4);
;         }
;         float s = 0.f;
; #pragma unroll
;         for (int j = 0; j < 8; ++j) s += (v[j][0] * v[j][0] + v[j][1] * v[j][1]) + (v[j][2] * v[j][2] + v[j][3] * v[j][3]);
;         const float rs = 1.0f / sqrtf(wave_sum(s) * (1.0f / D) + EPS);
.LBB0_1255:
	v_lshl_add_u64 v[4:5], s[28:29], 0, v[48:49]
	global_load_dwordx4 v[32:35], v[4:5], off
	global_load_dwordx4 v[28:31], v[4:5], off offset:1024
	global_load_dwordx4 v[24:27], v[4:5], off offset:2048
	global_load_dwordx4 v[20:23], v[4:5], off offset:3072
	v_add_co_u32_e32 v4, vcc, 0x1000, v4
	s_nop 0
	v_addc_co_u32_e32 v5, vcc, 0, v5, vcc
	global_load_dwordx4 v[16:19], v[4:5], off
	global_load_dwordx4 v[12:15], v[4:5], off offset:1024
	global_load_dwordx4 v[8:11], v[4:5], off offset:2048
	s_nop 0
	global_load_dwordx4 v[4:7], v[4:5], off offset:3072
	global_load_dwordx4 v[120:123], v[36:37], off
	global_load_dwordx4 v[124:127], v[36:37], off offset:1024
	global_load_dwordx4 v[128:131], v[36:37], off offset:2048
	global_load_dwordx4 v[132:135], v[36:37], off offset:3072
	global_load_dwordx4 v[136:139], v[38:39], off
	global_load_dwordx4 v[140:143], v[40:41], off
	global_load_dwordx4 v[144:147], v[42:43], off
	global_load_dwordx4 v[148:151], v[44:45], off
	s_waitcnt vmcnt(0)
	v_add_u32_e32 v0, s50, v0
	v_lshl_add_u64 v[48:49], v[48:49], 0, s[34:35]
	v_mov_b32_e32 v58, v33
	v_mov_b32_e32 v59, v29
	v_mov_b32_e32 v56, v32
	v_mov_b32_e32 v57, v28
	v_pk_mul_f32 v[58:59], v[58:59], v[58:59]
	v_mov_b32_e32 v60, v35
	v_mov_b32_e32 v61, v31
	v_pk_fma_f32 v[56:57], v[56:57], v[56:57], v[58:59]
	v_mov_b32_e32 v58, v34
	v_mov_b32_e32 v59, v30
	v_pk_mul_f32 v[60:61], v[60:61], v[60:61]
	v_mul_f32_e32 v1, v16, v16
	v_pk_fma_f32 v[58:59], v[58:59], v[58:59], v[60:61]
	v_pk_mul_f32 v[60:61], v[24:25], v[24:25]
	v_pk_add_f32 v[56:57], v[56:57], v[58:59]
	v_pk_mul_f32 v[58:59], v[26:27], v[26:27]
	v_mul_f32_e32 v50, v17, v17
	v_pk_mov_b32 v[62:63], v[60:61], v[58:59] op_sel:[1,0]
	v_mov_b32_e32 v61, v59
	v_pk_add_f32 v[58:59], v[62:63], v[60:61]
	v_pk_add_f32 v[56:57], v[56:57], v[56:57] op_sel:[0,1] op_sel_hi:[1,0]
	v_pk_add_f32 v[58:59], v[58:59], v[58:59] op_sel:[0,1] op_sel_hi:[1,0]
	v_mov_b32_e32 v57, v1
	v_mov_b32_e32 v59, v50
	v_mul_f32_e32 v50, v21, v21
	v_mul_f32_e32 v60, v18, v18
	v_pk_add_f32 v[56:57], v[56:57], v[58:59]
	v_pk_fma_f32 v[58:59], v[20:21], v[20:21], v[50:51] op_sel_hi:[1,1,0]
	v_mul_f32_e32 v50, v23, v23
	v_mul_f32_e32 v62, v19, v19
	v_mov_b32_e32 v59, v60
	v_pk_fma_f32 v[60:61], v[22:23], v[22:23], v[50:51] op_sel_hi:[1,1,0]
	v_mul_f32_e32 v1, v4, v4
	v_mov_b32_e32 v61, v62
	v_pk_add_f32 v[58:59], v[58:59], v[60:61]
	v_pk_mul_f32 v[60:61], v[12:13], v[12:13]
	v_pk_add_f32 v[56:57], v[56:57], v[58:59]
	v_pk_mul_f32 v[58:59], v[14:15], v[14:15]
	v_mul_f32_e32 v50, v5, v5
	v_pk_mov_b32 v[62:63], v[60:61], v[58:59] op_sel:[1,0]
	v_mov_b32_e32 v61, v59
	v_pk_add_f32 v[58:59], v[62:63], v[60:61]
	v_pk_add_f32 v[56:57], v[56:57], v[56:57] op_sel:[0,1] op_sel_hi:[1,0]
	v_pk_add_f32 v[58:59], v[58:59], v[58:59] op_sel:[0,1] op_sel_hi:[1,0]
	v_mov_b32_e32 v57, v1
	v_mov_b32_e32 v59, v50
	v_mul_f32_e32 v50, v9, v9
	v_mul_f32_e32 v60, v6, v6
	v_pk_add_f32 v[56:57], v[56:57], v[58:59]
	v_pk_fma_f32 v[58:59], v[8:9], v[8:9], v[50:51] op_sel_hi:[1,1,0]
	v_mul_f32_e32 v50, v11, v11
	v_mul_f32_e32 v62, v7, v7
	v_mov_b32_e32 v59, v60
	v_pk_fma_f32 v[60:61], v[10:11], v[10:11], v[50:51] op_sel_hi:[1,1,0]
	s_nop 0
	v_mov_b32_e32 v61, v62
	v_pk_add_f32 v[58:59], v[58:59], v[60:61]
	s_nop 0
	v_pk_add_f32 v[56:57], v[56:57], v[58:59]
	s_nop 0
	v_add_f32_e32 v1, v56, v57
	ds_bpermute_b32 v50, v3, v1
	s_waitcnt lgkmcnt(0)
	v_add_f32_e32 v1, v1, v50
	ds_bpermute_b32 v50, v51, v1
	s_waitcnt lgkmcnt(0)
	v_add_f32_e32 v1, v1, v50
	ds_bpermute_b32 v50, v52, v1
	s_waitcnt lgkmcnt(0)
	v_add_f32_e32 v1, v1, v50
	ds_bpermute_b32 v50, v53, v1
	s_waitcnt lgkmcnt(0)
	v_add_f32_e32 v1, v1, v50
	ds_bpermute_b32 v50, v54, v1
	s_waitcnt lgkmcnt(0)
	v_add_f32_e32 v1, v1, v50
	ds_bpermute_b32 v50, v55, v1
	s_waitcnt lgkmcnt(0)
; __device__ __forceinline__ unsigned pk2(float lo, float hi) { const f32x2 v = {lo, hi}; const bf16v2 b = __builtin_convertvector(v, bf16v2); return __builtin_bit_cast(unsigned, b); }
; #define p (*kparams())
; __device__ __forceinline__ void norm_rows(CParams& p, int mode, const float* gain, int nrows) {
;     ...
;         const float rs = 1.0f / sqrtf(wave_sum(s) * (1.0f / D) + EPS);
; #pragma unroll
;         for (int j = 0; j < 8; ++j) {
;             const f32x4 g = *(const f32x4*)(gain + (lane + 64 * j) * 4);
;             const f32x4 y = v[j] * rs * g;
;             if (mode == 3) *(f32x4*)(p.out + (size_t)row * D + (lane + 64 * j) * 4) = y;
;             else { u32x2 w; w.x = pk2(y[0], y[1]); w.y = pk2(y[2], y[3]); *(u32x2*)(NB + (size_t)row * D + (lane + 64 * j) * 4) = w; }
;         }
	v_add_f32_e32 v1, v1, v50
	v_fmamk_f32 v1, v1, 0x3a000000, v208
	v_cmp_gt_f32_e32 vcc, s88, v1
	v_mul_f32_e32 v50, 0x4f800000, v1
	s_nop 0
	v_cndmask_b32_e32 v1, v1, v50, vcc
	v_sqrt_f32_e32 v50, v1
	s_nop 0
	v_add_u32_e32 v56, -1, v50
	v_fma_f32 v57, -v56, v50, v1
	v_cmp_ge_f32_e64 s[42:43], 0, v57
	v_add_u32_e32 v57, 1, v50
	s_nop 0
	v_cndmask_b32_e64 v56, v50, v56, s[42:43]
	v_fma_f32 v50, -v57, v50, v1
	v_cmp_lt_f32_e64 s[42:43], 0, v50
	s_nop 1
	v_cndmask_b32_e64 v50, v56, v57, s[42:43]
	v_mul_f32_e32 v56, 0x37800000, v50
	v_cndmask_b32_e32 v50, v50, v56, vcc
	v_cmp_class_f32_e32 vcc, v1, v209
	s_nop 1
	v_cndmask_b32_e32 v1, v50, v1, vcc
	v_div_scale_f32 v50, s[10:11], v1, v1, 1.0
	v_rcp_f32_e32 v56, v50
	s_mov_b32 s10, 0x8200000
	v_fma_f32 v57, -v50, v56, 1.0
	v_fmac_f32_e32 v56, v57, v56
	v_div_scale_f32 v57, vcc, 1.0, v1, 1.0
	v_mul_f32_e32 v58, v57, v56
	v_fma_f32 v59, -v50, v58, v57
	v_fmac_f32_e32 v58, v59, v56
	v_fma_f32 v50, -v50, v58, v57
	v_div_fmas_f32 v50, v50, v56, v58
	v_div_fixup_f32 v50, v50, v1, 1.0
	v_pk_mul_f32 v[32:33], v[32:33], v[50:51] op_sel_hi:[1,0]
	v_pk_mul_f32 v[34:35], v[34:35], v[50:51] op_sel_hi:[1,0]
	v_pk_mul_f32 v[28:29], v[28:29], v[50:51] op_sel_hi:[1,0]
	v_pk_mul_f32 v[30:31], v[30:31], v[50:51] op_sel_hi:[1,0]
	v_pk_mul_f32 v[24:25], v[24:25], v[50:51] op_sel_hi:[1,0]
	v_pk_mul_f32 v[26:27], v[26:27], v[50:51] op_sel_hi:[1,0]
	v_pk_mul_f32 v[20:21], v[20:21], v[50:51] op_sel_hi:[1,0]
	v_pk_mul_f32 v[22:23], v[22:23], v[50:51] op_sel_hi:[1,0]
	v_pk_mul_f32 v[16:17], v[16:17], v[50:51] op_sel_hi:[1,0]
	v_pk_mul_f32 v[18:19], v[18:19], v[50:51] op_sel_hi:[1,0]
	v_pk_mul_f32 v[12:13], v[12:13], v[50:51] op_sel_hi:[1,0]
	v_pk_mul_f32 v[14:15], v[14:15], v[50:51] op_sel_hi:[1,0]
	v_pk_mul_f32 v[8:9], v[8:9], v[50:51] op_sel_hi:[1,0]
	v_pk_mul_f32 v[10:11], v[10:11], v[50:51] op_sel_hi:[1,0]
	v_pk_mul_f32 v[4:5], v[4:5], v[50:51] op_sel_hi:[1,0]
	v_pk_mul_f32 v[6:7], v[6:7], v[50:51] op_sel_hi:[1,0]
	v_pk_mul_f32 v[32:33], v[120:121], v[32:33]
	v_pk_mul_f32 v[58:59], v[122:123], v[34:35]
	v_cvt_pk_bf16_f32 v34, v32, v33
	v_lshl_add_u64 v[32:33], s[28:29], 0, v[46:47]
	v_add_co_u32_e32 v32, vcc, s10, v32
	v_cvt_pk_bf16_f32 v35, v58, v59
	s_nop 0
	v_addc_co_u32_e32 v33, vcc, 0, v33, vcc
	global_store_dwordx2 v[32:33], v[34:35], off
	v_cmp_le_i32_e32 vcc, s8, v0
	v_lshl_add_u64 v[46:47], v[46:47], 0, s[40:41]
	s_or_b64 s[30:31], vcc, s[30:31]
	v_pk_mul_f32 v[30:31], v[126:127], v[30:31]
	v_pk_mul_f32 v[28:29], v[124:125], v[28:29]
	s_nop 0
	v_cvt_pk_bf16_f32 v28, v28, v29
	v_cvt_pk_bf16_f32 v29, v30, v31
	global_store_dwordx2 v[32:33], v[28:29], off offset:512
	v_pk_mul_f32 v[26:27], v[130:131], v[26:27]
	v_pk_mul_f32 v[24:25], v[128:129], v[24:25]
	s_nop 0
	v_cvt_pk_bf16_f32 v24, v24, v25
	v_cvt_pk_bf16_f32 v25, v26, v27
	global_store_dwordx2 v[32:33], v[24:25], off offset:1024
	v_pk_mul_f32 v[22:23], v[134:135], v[22:23]
	v_pk_mul_f32 v[20:21], v[132:133], v[20:21]
	s_nop 0
	v_cvt_pk_bf16_f32 v20, v20, v21
	v_cvt_pk_bf16_f32 v21, v22, v23
	global_store_dwordx2 v[32:33], v[20:21], off offset:1536
	v_pk_mul_f32 v[18:19], v[138:139], v[18:19]
	v_pk_mul_f32 v[16:17], v[136:137], v[16:17]
	s_nop 0
	v_cvt_pk_bf16_f32 v16, v16, v17
	v_cvt_pk_bf16_f32 v17, v18, v19
	global_store_dwordx2 v[32:33], v[16:17], off offset:2048
	v_pk_mul_f32 v[14:15], v[142:143], v[14:15]
	v_pk_mul_f32 v[12:13], v[140:141], v[12:13]
	s_nop 0
	v_cvt_pk_bf16_f32 v12, v12, v13
	v_cvt_pk_bf16_f32 v13, v14, v15
	global_store_dwordx2 v[32:33], v[12:13], off offset:2560
	v_pk_mul_f32 v[10:11], v[10:11], v[146:147]
	v_pk_mul_f32 v[8:9], v[8:9], v[144:145]
	s_nop 0
	v_cvt_pk_bf16_f32 v8, v8, v9
	v_cvt_pk_bf16_f32 v9, v10, v11
	global_store_dwordx2 v[32:33], v[8:9], off offset:3072
	v_pk_mul_f32 v[6:7], v[6:7], v[150:151]
	v_pk_mul_f32 v[4:5], v[4:5], v[148:149]
	s_nop 0
	v_cvt_pk_bf16_f32 v4, v4, v5
	v_cvt_pk_bf16_f32 v5, v6, v7
	global_store_dwordx2 v[32:33], v[4:5], off offset:3584
	v_mov_b32_e32 v56, v124
	v_mov_b32_e32 v57, v125
	v_mov_b32_e32 v58, v126
	v_mov_b32_e32 v59, v127
	v_mov_b32_e32 v28, v128
	v_mov_b32_e32 v29, v129
	v_mov_b32_e32 v30, v130
	v_mov_b32_e32 v31, v131
	v_mov_b32_e32 v24, v132
	v_mov_b32_e32 v25, v133
	v_mov_b32_e32 v26, v134
	v_mov_b32_e32 v27, v135
	v_mov_b32_e32 v20, v136
	v_mov_b32_e32 v21, v137
	v_mov_b32_e32 v22, v138
	v_mov_b32_e32 v23, v139
	v_mov_b32_e32 v16, v140
	v_mov_b32_e32 v17, v141
	v_mov_b32_e32 v18, v142
	v_mov_b32_e32 v19, v143
	v_mov_b32_e32 v12, v144
	v_mov_b32_e32 v13, v145
	v_mov_b32_e32 v14, v146
	v_mov_b32_e32 v15, v147
	v_mov_b32_e32 v10, v150
	v_mov_b32_e32 v11, v151
	v_mov_b32_e32 v8, v148
	v_mov_b32_e32 v9, v149
	s_andn2_b64 exec, exec, s[30:31]
	s_cbranch_execnz .LBB0_1255
	s_branch .LBB0_1252
